# deferred tail: last 36 sample-attention units run on P3's idle CUs instead of P1's side CUs
# speedup vs baseline: 1.0065x; 1.0052x over previous
; #define LAS __attribute__((address_space(3)))
; __device__ __forceinline__ void attn_sample_head_unit(Frame& F, int unit) {
;     const int b = unit >> 2, head = unit & 3;
;     unsigned ln = (unsigned)F.lane; asm volatile("" : "+v"(ln));
;     const unsigned hk = ln >> 5, e0 = (ln & 31u) * 4u;
;     const bf16_t* Q = WSP(bf16_t, WS_Q); const bf16_t* SGC = WSP(bf16_t, WS_SGC); bf16_t* CAT = WSP(bf16_t, WS_CAT);
;     LAS float* SL = (LAS float*)F.lds;
;     LAS float* OL = (LAS float*)(F.lds + 4096);
; __global__ void __launch_bounds__(NTHR, 2) hybrid_fwd(Args args) {
;     ...
;     if ((int)blockIdx.x >= NAS_FREE_FROM && (int)gridDim.x == 256) {
;         Frame F = make_frame(lds);
;         if (F.tid < 64) { unsigned* fl = (unsigned*)(F.ws + WS_CTL) + CW_QREADY; unsigned sp = 0;
;             while (__hip_atomic_load(fl, __ATOMIC_RELAXED, __HIP_MEMORY_SCOPE_AGENT) < (unsigned)G1_SPECIAL) { __builtin_amdgcn_s_sleep(4); if (++sp > (1u << 22)) break; }
;             __builtin_amdgcn_fence(__ATOMIC_ACQUIRE, "agent"); }
;         asm volatile("s_waitcnt vmcnt(0)" ::: "memory"); __syncthreads();
;         for (int u = (int)blockIdx.x - NAS_FREE_FROM; u < NAS_UNITS; u += 256 - NAS_FREE_FROM) attn_sample_head_unit(F, u);
.LBB0_282:
	s_or_b64 exec, exec, s[6:7]
	s_waitcnt vmcnt(0)
	s_cmpk_gt_i32 s2, 0x2df
	s_waitcnt vmcnt(0) lgkmcnt(0)
	s_barrier
	s_cbranch_scc1 .LBB0_311
	s_ashr_i32 s20, s12, 6
	s_lshl_b32 s6, s20, 2
	s_add_i32 s12, s6, 0
	s_sub_i32 s29, s2, 0xe0
	s_movk_i32 s100, 0x20
	s_movk_i32 s101, 0x1bc
	s_bitcmp1_b32 s98, 6
	s_cbranch_scc0 .Lattn_p1
	s_add_i32 s29, s2, 0x100
	s_movk_i32 s100, 36
	s_movk_i32 s101, 0x1dc
.Lattn_p1:
	s_add_u32 s13, s10, 0x9200000
	s_addc_u32 s34, s11, 0
	s_add_u32 s22, s10, 0xa300000
	s_addc_u32 s23, s11, 0
	s_lshl_b32 s6, s20, 5
	s_ashr_i32 s7, s6, 31
	s_lshl_b64 s[8:9], s[6:7], 10
	s_lshl_b32 s6, s20, 9
	s_add_i32 s35, s6, 0
	s_cmp_lt_i32 s20, 4
	s_cselect_b64 s[40:41], -1, 0
	s_lshl_b32 s6, s20, 12
	s_add_i32 s36, s6, 0
	s_movk_i32 s6, 0x100
	v_and_b32_e32 v1, 63, v2
	v_cmp_gt_i32_e64 s[6:7], s6, v2
	v_ashrrev_i32_e32 v102, 6, v2
	v_lshlrev_b32_e32 v2, 2, v2
	v_and_b32_e32 v103, 0xfc, v2
	v_lshlrev_b32_e32 v2, 10, v102
	v_lshlrev_b32_e32 v3, 2, v103
	v_add3_u32 v104, 0, v2, v3
	v_mbcnt_lo_u32_b32 v2, -1, 0
	s_mov_b32 s21, 0
	v_mov_b32_e32 v59, 0
	s_mov_b64 s[42:43], 0x1000800
	s_mov_b32 s37, 0x1000000
	s_mov_b64 s[44:45], 0x1001000
	s_mov_b32 s58, 0x1001000
	s_mov_b64 s[46:47], 0x1001800
	s_lshl_b64 s[48:49], s[8:9], 2
	s_mov_b32 s59, 0xff61b1e6
	v_mbcnt_hi_u32_b32 v105, -1, v2
	s_branch .LBB0_285
.LBB0_284:
	s_or_b64 exec, exec, s[8:9]
	s_waitcnt lgkmcnt(0)
	s_add_i32 s8, s29, s100
	s_cmp_lt_i32 s29, s101
	s_mov_b32 s29, s8
	s_barrier
	s_cbranch_scc0 .LBB0_311

; __global__ void __launch_bounds__(NTHR, 2) hybrid_fwd(Args args) {
;     ...
;         for (int u = (int)blockIdx.x - NAS_FREE_FROM; u < NAS_UNITS; u += 256 - NAS_FREE_FROM) attn_sample_head_unit(F, u);
;     }
;     {
;         constexpr int NFREE = 256 - NAS_FREE_FROM, N3 = NAS_UNITS - 2 * NFREE, NLATE = NFREE - N3;
;         const int idx = (int)blockIdx.x - NAS_FREE_FROM - N3;
;         if (idx >= 0 && (int)gridDim.x == 256) { Frame F = make_frame(lds);
;             p0_items(F, NITEMS_EARLY, NITEMS, idx * NWAVES + F.wave, NLATE * NWAVES);
;             p0_pool_pad(F, idx * NTHR + F.tid, NLATE * NTHR); p0_pool_frag(F, idx * NTHR + F.tid, NLATE * NTHR); }
;     }
;     if ((int)blockIdx.x >= NAS_FREE_FROM && (int)gridDim.x == 256) {
;         Frame F = make_frame(lds); states_copy_rows(F, ((int)blockIdx.x - NAS_FREE_FROM) * NWAVES + F.wave, (256 - NAS_FREE_FROM) * NWAVES); }
.LBB0_311:
	s_bitcmp1_b32 s98, 6
	s_cbranch_scc0 .Lnot_p3
	s_mov_b32 s98, 0
	s_branch .LBB0_670

; __global__ void __launch_bounds__(NTHR, 2) hybrid_fwd(Args args) {
;     ...
;     { Frame F = make_frame(lds);
;       Epi3<1> E{WSP(bf16_t, WS_SGA), WSP(bf16_t, WS_SGB), F.in[13], WSP(bf16_t, WS_CAT)};
;       Sched3pl Sp{F.G, (int)((blockIdx.x + 52) % F.G), (const char*)(F.ws + WS_POOLED), (const char*)(F.ws + WS_WPOOL)};
;       pg8::gemm_phase<Epi3<1>, Sched3pl, true, true>(F.lds, DPOOL, PGRP, Sp, E); }
.Lp3_attn:
	s_cmpk_lt_u32 s2, 0xdc
	s_cbranch_scc1 .LBB0_670
	s_mov_b32 s98, 0x40
	s_branch .Lside_attn
